# XCD barrier: L1 invalidate issued before the spin waits instead of after the release (off the critical path)
# speedup vs baseline: 1.0181x; 1.0181x over previous
; __device__ __forceinline__ unsigned xb_ld(unsigned* p)              { return __hip_atomic_load(p, __ATOMIC_RELAXED, __HIP_MEMORY_SCOPE_AGENT); }
; __device__ __forceinline__ unsigned xb_add(unsigned* p, unsigned v) { return __hip_atomic_fetch_add(p, v, __ATOMIC_RELAXED, __HIP_MEMORY_SCOPE_AGENT); }
; #define XB_SPIN(cond, bar) do { unsigned _sp = 0; while (cond) { __builtin_amdgcn_s_sleep(1); \
;     if ((++_sp & 255u) == 0u) { if (xb_ld(&(bar)[XB_TMO])) break; if (_sp > XB_SPIN_CAP) { atomicAdd(&(bar)[XB_TMO], 1u); break; } } } } while (0)
; __device__ __forceinline__ void xcd_barrier(const XcdBarrier& b) {
;     ...
;         if (nloc == 0u) { xcd_barrier_complete(bar, b.x, nloc, nx); b.st[0] = nloc; b.st[1] = nx; }
;         const unsigned old = xb_add(&bar[XB_XSUB(b.x)], 1u);
;         const unsigned gen = old / nloc;
;         if (old + 1u == (gen + 1u) * nloc) {
;     ...
;         } else {
;             XB_SPIN(xb_ld(&bar[XB_XGEN(b.x)]) == gen, bar);
;             __builtin_amdgcn_fence(__ATOMIC_ACQUIRE, "agent");
;             asm volatile("s_waitcnt vmcnt(0)" ::: "memory");
.LBB0_569:
	s_or_b64 exec, exec, s[12:13]
	v_cvt_f32_u32_e32 v5, v3
	s_waitcnt vmcnt(0)
	v_readfirstlane_b32 s10, v4
	v_sub_u32_e32 v4, 0, v3
	v_rcp_iflag_f32_e32 v5, v5
	v_add_u32_e32 v6, s10, v1
	v_mul_f32_e32 v5, 0x4f7ffffe, v5
	v_cvt_u32_f32_e32 v5, v5
	v_mul_lo_u32 v1, v4, v5
	v_mul_hi_u32 v1, v5, v1
	v_add_u32_e32 v1, v5, v1
	v_mul_hi_u32 v1, v6, v1
	v_mul_lo_u32 v4, v1, v3
	v_sub_u32_e32 v4, v6, v4
	v_add_u32_e32 v5, 1, v1
	v_cmp_ge_u32_e32 vcc, v4, v3
	s_nop 1
	v_cndmask_b32_e32 v1, v1, v5, vcc
	v_sub_u32_e32 v5, v4, v3
	v_cndmask_b32_e32 v4, v4, v5, vcc
	v_add_u32_e32 v5, 1, v1
	v_cmp_ge_u32_e32 vcc, v4, v3
	v_add_u32_e32 v4, 1, v6
	s_nop 0
	v_cndmask_b32_e32 v1, v1, v5, vcc
	v_mul_lo_u32 v5, v3, v1
	v_add_u32_e32 v3, v5, v3
	v_cmp_ne_u32_e32 vcc, v4, v3
	s_and_saveexec_b64 s[10:11], vcc
	s_xor_b64 s[12:13], exec, s[10:11]
	s_cbranch_execz .LBB0_583
	buffer_inv sc1
	v_readlane_b32 s10, v255, 11
	v_readlane_b32 s11, v255, 12
	s_waitcnt lgkmcnt(0)
	s_nop 3
	global_load_dword v0, v2, s[10:11] sc1
	s_waitcnt vmcnt(0)
	v_cmp_eq_u32_e32 vcc, v0, v1
	s_and_saveexec_b64 s[38:39], vcc
	s_cbranch_execz .LBB0_582
	s_mov_b32 s10, 1
	s_mov_b64 s[40:41], 0
	s_branch .LBB0_573

; __device__ __forceinline__ unsigned xb_ld(unsigned* p)              { return __hip_atomic_load(p, __ATOMIC_RELAXED, __HIP_MEMORY_SCOPE_AGENT); }
; #define XB_SPIN(cond, bar) do { unsigned _sp = 0; while (cond) { __builtin_amdgcn_s_sleep(1); \
;     if ((++_sp & 255u) == 0u) { if (xb_ld(&(bar)[XB_TMO])) break; if (_sp > XB_SPIN_CAP) { atomicAdd(&(bar)[XB_TMO], 1u); break; } } } } while (0)
; __device__ __forceinline__ void xcd_barrier(const XcdBarrier& b) {
;     ...
;         } else {
;             XB_SPIN(xb_ld(&bar[XB_XGEN(b.x)]) == gen, bar);
;             __builtin_amdgcn_fence(__ATOMIC_ACQUIRE, "agent");
;             asm volatile("s_waitcnt vmcnt(0)" ::: "memory");
;         }
.LBB0_582:
	s_or_b64 exec, exec, s[38:39]
	s_waitcnt vmcnt(0)
	s_waitcnt vmcnt(0)

; __device__ __forceinline__ unsigned xb_ld(unsigned* p)              { return __hip_atomic_load(p, __ATOMIC_RELAXED, __HIP_MEMORY_SCOPE_AGENT); }
; __device__ __forceinline__ unsigned xb_add(unsigned* p, unsigned v) { return __hip_atomic_fetch_add(p, v, __ATOMIC_RELAXED, __HIP_MEMORY_SCOPE_AGENT); }
; #define XB_SPIN(cond, bar) do { unsigned _sp = 0; while (cond) { __builtin_amdgcn_s_sleep(1); \
;     if ((++_sp & 255u) == 0u) { if (xb_ld(&(bar)[XB_TMO])) break; if (_sp > XB_SPIN_CAP) { atomicAdd(&(bar)[XB_TMO], 1u); break; } } } } while (0)
; __device__ __forceinline__ void xcd_barrier(const XcdBarrier& b) {
;     ...
;             const unsigned og = xb_add(&bar[XB_TOP], 1u);
;             const unsigned tg = og / nx;
;             if (og + 1u == (tg + 1u) * nx) xb_add(&bar[XB_TOPGEN], 1u);
;             else XB_SPIN(xb_ld(&bar[XB_TOPGEN]) == tg, bar);
;             __builtin_amdgcn_fence(__ATOMIC_ACQUIRE, "agent");
.LBB0_586:
	s_or_b64 exec, exec, s[38:39]
	s_waitcnt vmcnt(0)
	buffer_inv sc1
	v_readfirstlane_b32 s10, v3
	v_cvt_f32_u32_e32 v3, v0
	v_sub_u32_e32 v4, 0, v0
	v_add_u32_e32 v1, s10, v1
	v_readlane_b32 s10, v255, 15
	v_rcp_iflag_f32_e32 v3, v3
	v_readlane_b32 s11, v255, 16
	s_mov_b64 s[38:39], -1
	v_mul_f32_e32 v3, 0x4f7ffffe, v3
	v_cvt_u32_f32_e32 v3, v3
	v_mul_lo_u32 v4, v4, v3
	v_mul_hi_u32 v4, v3, v4
	v_add_u32_e32 v3, v3, v4
	v_mul_hi_u32 v3, v1, v3
	v_mul_lo_u32 v4, v3, v0
	v_sub_u32_e32 v4, v1, v4
	v_cmp_ge_u32_e32 vcc, v4, v0
	v_add_u32_e32 v5, 1, v3
	v_add_u32_e32 v1, 1, v1
	v_cndmask_b32_e32 v3, v3, v5, vcc
	v_sub_u32_e32 v5, v4, v0
	v_cndmask_b32_e32 v4, v4, v5, vcc
	v_cmp_ge_u32_e32 vcc, v4, v0
	v_add_u32_e32 v4, 1, v3
	s_nop 0
	v_cndmask_b32_e32 v3, v3, v4, vcc
	v_mul_lo_u32 v4, v0, v3
	v_add_u32_e32 v0, v4, v0
	v_cmp_ne_u32_e32 vcc, v1, v0
	v_mov_b64_e32 v[0:1], s[10:11]
	s_and_saveexec_b64 s[12:13], vcc
	s_cbranch_execz .LBB0_598
	v_readlane_b32 s10, v255, 15
	v_readlane_b32 s11, v255, 16
	s_mov_b64 s[40:41], 0
	s_nop 3
	global_load_dword v0, v2, s[10:11] sc1
	s_waitcnt vmcnt(0)
	v_cmp_eq_u32_e32 vcc, v0, v3
	s_and_saveexec_b64 s[38:39], vcc
	s_cbranch_execz .LBB0_597
	s_mov_b32 s10, 1
	s_branch .LBB0_590

; __device__ __forceinline__ unsigned xb_add(unsigned* p, unsigned v) { return __hip_atomic_fetch_add(p, v, __ATOMIC_RELAXED, __HIP_MEMORY_SCOPE_AGENT); }
; __device__ __forceinline__ void xcd_barrier(const XcdBarrier& b) {
;     ...
;             __builtin_amdgcn_fence(__ATOMIC_ACQUIRE, "agent");
;             xb_add(&bar[XB_XGEN(b.x)], 1u);
;             asm volatile("s_waitcnt vmcnt(0)" ::: "memory");
.LBB0_600:
	s_or_b64 exec, exec, s[12:13]
	s_mov_b64 s[12:13], exec
	v_mbcnt_lo_u32_b32 v0, s12, 0
	v_mbcnt_hi_u32_b32 v0, s13, v0
	v_cmp_eq_u32_e32 vcc, 0, v0
	s_and_saveexec_b64 s[38:39], vcc
	s_cbranch_execz .LBB0_602
	s_bcnt1_i32_b64 s10, s[12:13]
	v_mov_b32_e32 v0, s10
	v_readlane_b32 s10, v255, 11
	v_readlane_b32 s11, v255, 12
	s_nop 4
	global_atomic_add v2, v0, s[10:11]
